# v63 + attention tile-loop back edge rotated in front of the closing barrier (barrier falls into the loop head ds_reads)
# speedup vs baseline: 1.0006x; 1.0006x over previous
; __device__ __forceinline__ void attn_unit(const bf16_t* __restrict__ Qs, const bf16_t* __restrict__ Kn, const bf16_t* __restrict__ Kr, const bf16_t* __restrict__ Vs, bf16_t* Os, int q0, int Lp, char* lds, const int tid) {
;     const int wid = tid >> 6, lane = tid & 63, r32 = lane & 31, hi = lane >> 5; const int wu = __builtin_amdgcn_readfirstlane(wid);
;     char* V_lds = lds; char* K_lds = lds + 2 * SHM_V;
;     float* ws = (float*)(lds + 2 * SHM_V + 2 * SHM_K) + wid * 64; float* li_l = ws; float* al_l = ws + 32;
;     float m_reg = -1e30f, l_reg = 0; f32x16 o[4] = {}; bf16x8 qr[12 - NQL];
;     char* qslot = lds + SHM_QR + wid * (NQL * 1024) + lane * 16;
;     int kb[4];
; #pragma unroll
;     for (int c = 0; c < 4; ++c) kb[c] = KSWZ(r32, c * 32 + hi * 16);
;     const bf16_t* ksrc[3];
; #pragma unroll
;     for (int n = 0; n < 3; ++n) { const int p = (wid * 3 + n) * 64 + lane, row = p / 24, cp = p % 24, c = (cp & 24) | ((cp ^ row) & 7);
;         ksrc[n] = c < 16 ? Kn + (size_t)row * 2048 + c * 8 : Kr + (size_t)row * 64 + (c - 16) * 8; }
;     unsigned vsrc[2];
; #pragma unroll
;     for (int n = 0; n < 2; ++n) { const int p = (wid * 2 + n) * 64 + lane, sub = p >> 5, elt = (p & 31) * 8, kk = (sub >> 2) * 8 + (elt >> 5), k = (kk & ~0xC) | ((kk & 4) << 1) | ((kk & 8) >> 1), c = (sub & 3) * 32 + (elt & 31);
;         vsrc[n] = (unsigned)(k * 2048 + c) * 2u; }
;     const unsigned lK = (unsigned)(uintptr_t)K_lds + wu * 3072, lV = (unsigned)(uintptr_t)V_lds + wu * 2048;
;     bool krope[3];
; #pragma unroll
; __device__ __forceinline__ void attn_phase(const Frame& F, const bf16_t* Q, const bf16_t* KN, const bf16_t* KR, const bf16_t* V, bf16_t* O) {
;     ...
;         if (exact) { smp = i >= np; u = !smp ? (i < 8 ? c + 256 * i : 2048 + c) : (c < 64 ? c + 64 * (i - np) : 448 + (c - 64) + 192 * (i - np)); }
;         else { const int g = c + F.G * i; smp = g >= NUP; u = smp ? g - NUP : g; }
;         const int nqb = smp ? NQS : NQP, Lp = smp ? LP_S : LP_P;
;         const int qb = u % nqb, sh = u / nqb, head = sh % MH, seq = sh / MH; const size_t rb = (smp ? (size_t)ROWS0 : 0) + (size_t)seq * Lp;
;         attn_unit(Q + rb * 3072 + head * MQK, KN + rb * 2048 + head * MNOPE, KR + rb * 64, V + rb * 2048 + head * MV, O + rb * 2048 + head * MV, qb * 256, Lp, F.ldsg, F.tid);
.LBB0_621:
	s_and_b64 s[22:23], s[0:1], exec
	s_cselect_b32 s13, 17, 33
	v_cvt_f32_ubyte0_e32 v0, s13
	v_rcp_iflag_f32_e32 v0, v0
	s_movk_i32 s22, 0x2080
	s_cselect_b32 s62, 0x1080, s22
	s_sub_i32 s30, 0, s13
	v_mul_f32_e32 v0, 0x4f7ffffe, v0
	v_cvt_u32_f32_e32 v0, v0
	s_abs_i32 s23, s12
	s_ashr_i32 s22, s12, 31
	s_movk_i32 s64, 0xff00
	v_readfirstlane_b32 s31, v0
	s_mul_i32 s30, s30, s31
	s_mul_hi_u32 s30, s31, s30
	s_add_i32 s31, s31, s30
	s_mul_hi_u32 s30, s23, s31
	s_mul_i32 s31, s30, s13
	s_sub_i32 s23, s23, s31
	s_add_i32 s42, s30, 1
	s_sub_i32 s31, s23, s13
	s_cmp_ge_u32 s23, s13
	s_cselect_b32 s30, s42, s30
	s_cselect_b32 s23, s31, s23
	s_add_i32 s31, s30, 1
	s_cmp_ge_u32 s23, s13
	s_cselect_b32 s23, s31, s30
	s_xor_b32 s23, s23, s22
	s_sub_i32 s22, s23, s22
	s_mul_i32 s13, s22, s13
	s_sub_i32 s48, s12, s13
	s_ashr_i32 s12, s22, 31
	s_lshr_b32 s12, s12, 28
	s_add_i32 s12, s22, s12
	s_ashr_i32 s13, s12, 4
	s_and_b32 s12, s12, -16
	s_sub_i32 s46, s22, s12
	s_and_b64 s[0:1], s[0:1], exec
	s_cselect_b32 s0, 0x8200, 0
	s_mul_hi_i32 s1, s13, s62
	s_mul_i32 s13, s13, s62
	s_add_u32 s12, s13, s0
	s_addc_u32 s13, s1, 0
	s_mul_i32 s0, s13, 0x1800
	s_mul_hi_u32 s1, s12, 0x1800
	s_add_i32 s1, s1, s0
	s_mul_i32 s0, s12, 0x1800
	s_add_u32 s22, s52, s0
	s_mul_i32 s0, s46, 0xc0
	s_addc_u32 s23, s53, s1
	s_ashr_i32 s1, s0, 31
	s_lshl_b64 s[0:1], s[0:1], 1
	s_add_u32 s42, s22, s0
	s_addc_u32 s43, s23, s1
	s_lshl_b64 s[22:23], s[12:13], 11
	s_lshl_b64 s[30:31], s[12:13], 12
	s_add_u32 s47, s54, s30
	s_addc_u32 s49, s55, s31
	s_lshl_b32 s0, s46, 7
	s_ashr_i32 s1, s0, 31
	s_lshl_b64 s[0:1], s[0:1], 1
	s_add_u32 s46, s47, s0
	s_addc_u32 s47, s49, s1
	s_lshl_b64 s[12:13], s[12:13], 7
	s_add_u32 s12, s60, s12
	s_addc_u32 s13, s61, s13
	v_lshl_add_u64 v[2:3], s[12:13], 0, v[198:199]
	v_lshl_add_u64 v[0:1], s[46:47], 0, v[200:201]
	v_lshl_add_u64 v[2:3], v[2:3], 0, v[192:193]
	s_mov_b32 s65, -1
	v_lshl_add_u64 v[0:1], v[0:1], 0, v[192:193]
	v_lshl_add_u64 v[2:3], v[2:3], 0, s[64:65]
	s_add_u32 s30, s11, s30
	v_cndmask_b32_e64 v229, v3, v1, s[34:35]
	v_cndmask_b32_e64 v228, v2, v0, s[34:35]
	v_mov_b32_e32 v217, v193
	v_lshl_add_u64 v[2:3], s[12:13], 0, v[202:203]
	s_addc_u32 s31, s18, s31
	v_lshl_add_u64 v[0:1], s[46:47], 0, v[204:205]
	v_lshl_add_u64 v[2:3], v[2:3], 0, v[216:217]
	s_add_u32 s30, s30, s0
	v_readfirstlane_b32 s49, v191
	v_lshl_add_u64 v[0:1], v[0:1], 0, v[216:217]
	v_lshl_add_u64 v[2:3], v[2:3], 0, s[64:65]
	s_addc_u32 s31, s31, s1
	v_cndmask_b32_e64 v231, v3, v1, s[36:37]
	v_cndmask_b32_e64 v230, v2, v0, s[36:37]
	v_mov_b32_e32 v219, v193
	v_lshl_add_u64 v[2:3], s[12:13], 0, v[206:207]
	s_lshl_b32 s12, s49, 11
	s_add_i32 s13, 0, 0x8000
	v_lshl_add_u64 v[0:1], s[46:47], 0, v[208:209]
	v_lshl_add_u64 v[2:3], v[2:3], 0, v[218:219]
	s_cmp_lg_u32 s13, -1
	v_lshl_add_u64 v[0:1], v[0:1], 0, v[218:219]
	v_lshl_add_u64 v[2:3], v[2:3], 0, s[64:65]
	s_mul_i32 s65, s49, 0xc00
	s_cselect_b32 s13, s13, 0
	v_mov_b32_e32 v221, v193
	v_cndmask_b32_e64 v233, v3, v1, s[38:39]
	v_cndmask_b32_e64 v232, v2, v0, s[38:39]
	s_add_i32 s65, s65, s13
	v_lshl_add_u64 v[0:1], v[228:229], 0, v[220:221]
	v_mov_b32_e32 v223, v193
	s_add_i32 s66, s65, 0x6000
	s_mov_b32 s13, m0
	s_mov_b32 m0, s66
	s_nop 0
	global_load_lds_dwordx4 v[0:1], off
	s_mov_b32 m0, s13
	v_lshl_add_u64 v[0:1], v[230:231], 0, v[222:223]
	v_mov_b32_e32 v225, v193
	s_add_i32 s67, s65, 0x6400
	s_mov_b32 s13, m0
	s_mov_b32 m0, s67
	s_nop 0
	global_load_lds_dwordx4 v[0:1], off
	s_mov_b32 m0, s13
	v_lshl_add_u64 v[0:1], v[232:233], 0, v[224:225]
	s_add_i32 s68, s65, 0x6800
	s_mov_b32 s13, m0
	s_mov_b32 m0, s68
	s_nop 0
	global_load_lds_dwordx4 v[0:1], off
	s_mov_b32 m0, s13
	v_lshlrev_b32_e32 v0, 5, v191
	s_cmp_lg_u32 0, -1
	v_lshl_add_u32 v217, s48, 8, v0
	s_cselect_b32 s13, 0, 0
	v_or_b32_e32 v2, v217, v190
	v_mov_b64_e32 v[0:1], s[42:43]
	s_add_i32 s69, s12, s13
	s_mov_b32 s12, m0
	s_mov_b32 m0, s69
	s_nop 0
	global_load_lds_dwordx4 v211, s[30:31]
	s_mov_b32 m0, s12
	v_mov_b32_e32 v227, v193
	v_mad_i64_i32 v[0:1], s[12:13], v2, s77, v[0:1]
	s_add_i32 s70, s69, 0x400
	s_mov_b32 s12, m0
	s_mov_b32 m0, s70
	s_nop 0
	global_load_lds_dwordx4 v213, s[30:31]
	s_mov_b32 m0, s12
	v_lshl_add_u64 v[0:1], v[0:1], 0, v[226:227]
	global_load_dwordx4 v[186:189], v[0:1], off
	global_load_dwordx4 v[182:185], v[0:1], off offset:32
	global_load_dwordx4 v[178:181], v[0:1], off offset:64
	global_load_dwordx4 v[174:177], v[0:1], off offset:96
	global_load_dwordx4 v[170:173], v[0:1], off offset:128
	global_load_dwordx4 v[166:169], v[0:1], off offset:160
	global_load_dwordx4 v[162:165], v[0:1], off offset:192
	global_load_dwordx4 v[158:161], v[0:1], off offset:224
	global_load_dwordx4 v[154:157], v[0:1], off offset:256
	global_load_dwordx4 v[150:153], v[0:1], off offset:288
	global_load_dwordx4 v[146:149], v[0:1], off offset:320
	global_load_dwordx4 v[142:145], v[0:1], off offset:352
	s_waitcnt vmcnt(0)
	s_lshr_b32 s71, s62, 6
	s_waitcnt lgkmcnt(0)
	s_barrier
; #define WAITV(N) asm volatile("s_waitcnt vmcnt(" #N ")" ::: "memory")
; #define LBAR() asm volatile("s_waitcnt lgkmcnt(0)\n\ts_barrier" ::: "memory")
; __device__ __forceinline__ void attn_unit(const bf16_t* __restrict__ Qs, const bf16_t* __restrict__ Kn, const bf16_t* __restrict__ Kr, const bf16_t* __restrict__ Vs, bf16_t* Os, int q0, int Lp, char* lds, const int tid) {
;     ...
;     f32x16 pA0, pA1, pB0, pB1; float alA = 1.f, alB; bf16x8 pa[4]; s16x4 vl[4], vh[4]; const int NT = Lp / KVBLK;
;     static_assert(PADF >= KVBLK && PADF < 2 * KVBLK, "tile 0 fully masked, tile 1 partly");
;     ...
;     pA0 = f32x16{};
; #pragma unroll
;     for (int r = 0; r < 16; ++r) pA1[r] = -INFINITY;
;     WAITV(0); LBAR();
;     for (int j = 1; j + 1 < NT; j += 2) {
	s_add_i32 s72, s65, 0x400
	s_add_i32 s73, s65, 0x800
	s_add_i32 s64, s69, 0x4000
	s_add_i32 s63, s69, 0x4400
	v_mov_b32_e32 v14, v193
	v_mov_b32_e32 v15, v193
	s_add_u32 s42, s30, 0x80000
	v_mov_b32_e32 v0, v193
	v_mov_b32_e32 v1, v193
	v_mov_b32_e32 v2, v193
	v_mov_b32_e32 v3, v193
	v_mov_b32_e32 v4, v193
	v_mov_b32_e32 v5, v193
	v_mov_b32_e32 v6, v193
	v_mov_b32_e32 v7, v193
	v_mov_b32_e32 v8, v193
	v_mov_b32_e32 v9, v193
	v_mov_b32_e32 v10, v193
	v_mov_b32_e32 v11, v193
	v_mov_b32_e32 v12, v193
	v_mov_b32_e32 v13, v193
	s_waitcnt vmcnt(0) lgkmcnt(0)
	v_mov_b32_e32 v64, 0xff800000
	v_mov_b32_e32 v219, 0
	v_mov_b64_e32 v[62:63], v[14:15]
	v_mov_b64_e32 v[46:47], v[14:15]
	v_mov_b64_e32 v[30:31], v[14:15]
	s_addc_u32 s43, s31, 0
	v_mov_b32_e32 v221, 1.0
	v_mov_b32_e32 v130, 0xf149f2ca
	s_mov_b64 s[46:47], 2
	v_mov_b64_e32 v[60:61], v[12:13]
	v_mov_b64_e32 v[58:59], v[10:11]
	v_mov_b64_e32 v[56:57], v[8:9]
	v_mov_b64_e32 v[54:55], v[6:7]
	v_mov_b64_e32 v[52:53], v[4:5]
	v_mov_b64_e32 v[50:51], v[2:3]
	v_mov_b64_e32 v[48:49], v[0:1]
	v_mov_b64_e32 v[44:45], v[12:13]
	v_mov_b64_e32 v[42:43], v[10:11]
	v_mov_b64_e32 v[40:41], v[8:9]
	v_mov_b64_e32 v[38:39], v[6:7]
	v_mov_b64_e32 v[36:37], v[4:5]
	v_mov_b64_e32 v[34:35], v[2:3]
	v_mov_b64_e32 v[32:33], v[0:1]
	v_mov_b64_e32 v[28:29], v[12:13]
	v_mov_b64_e32 v[26:27], v[10:11]
	v_mov_b64_e32 v[24:25], v[8:9]
	v_mov_b64_e32 v[22:23], v[6:7]
	v_mov_b64_e32 v[20:21], v[4:5]
	v_mov_b64_e32 v[18:19], v[2:3]
	v_mov_b64_e32 v[16:17], v[0:1]
	v_mov_b32_e32 v94, 0
	v_mov_b32_e32 v95, v219
	v_mov_b32_e32 v96, v219
	v_mov_b32_e32 v97, v219
	v_mov_b32_e32 v98, v219
	v_mov_b32_e32 v99, v219
	v_mov_b32_e32 v100, v219
	v_mov_b32_e32 v101, v219
	v_mov_b32_e32 v102, v219
	v_mov_b32_e32 v103, v219
	v_mov_b32_e32 v104, v219
	v_mov_b32_e32 v105, v219
	v_mov_b32_e32 v106, v219
	v_mov_b32_e32 v107, v219
	v_mov_b32_e32 v108, v219
	v_mov_b32_e32 v109, v219
	v_mov_b32_e32 v65, v64
	v_mov_b32_e32 v66, v64
	v_mov_b32_e32 v67, v64
	v_mov_b32_e32 v68, v64
	v_mov_b32_e32 v69, v64
	v_mov_b32_e32 v70, v64
	v_mov_b32_e32 v71, v64
	v_mov_b32_e32 v72, v64
	v_mov_b32_e32 v73, v64
	v_mov_b32_e32 v74, v64
	v_mov_b32_e32 v75, v64
	v_mov_b32_e32 v76, v64
	v_mov_b32_e32 v77, v64
	v_mov_b32_e32 v78, v64
	v_mov_b32_e32 v79, v64
	.p2align 6
	s_branch .LBB0_622
.Lattn_head_bar:
	s_waitcnt lgkmcnt(0)
	s_barrier

; #define SBAR() __builtin_amdgcn_sched_barrier(0)
; #define PIN2(A, B) asm volatile("" : "+v"(A), "+v"(B))
; #define WAITV(N) asm volatile("s_waitcnt vmcnt(" #N ")" ::: "memory")
; #define LBAR() asm volatile("s_waitcnt lgkmcnt(0)\n\ts_barrier" ::: "memory")
; #define RESC(a) do { if (__any((a) < 1.f)) { if (hi == 0) al_l[r32] = (a); asm volatile("s_waitcnt lgkmcnt(0)" ::: "memory"); \
;     _Pragma("unroll") for (int d = 0; d < 4; ++d) _Pragma("unroll") for (int r = 0; r < 16; ++r) o[d][r] *= al_l[crow(r, hi)]; } } while (0)
; #define DMA_FN(KT, KB, VT, VBUF) [&](auto pc_) { constexpr int pc = decltype(pc_)::value; \
;         if constexpr (pc < 3) glds16(ksrc[pc] + (size_t)(KT) * (krope[pc] ? KVBLK * 64 : KVBLK * 2048), lK + (KB) * SHM_K + pc * 1024); \
;         else rscan::glds16u(Vs + (size_t)(VT) * KVBLK * 2048, vsrc[pc - 3], lV + (VBUF) * SHM_V + (pc - 3) * 1024); }
; template <int M> __device__ __forceinline__ void fin_slice(f32x16& p0, f32x16& p1, float mreg, float alpha, float& l_reg, FinSt& st, bf16x8 (&pa)[4]) {
;     ...
;     else if constexpr (M == 22) { float ps = st.s0 + st.s1;
;         auto rr = __builtin_amdgcn_permlane32_swap(__float_as_uint(ps), __float_as_uint(ps), false, false); ps = __uint_as_float(rr[0]) + __uint_as_float(rr[1]);
;         l_reg = l_reg * alpha + ps; }
; __device__ __forceinline__ void attn_unit(const bf16_t* __restrict__ Qs, const bf16_t* __restrict__ Kn, const bf16_t* __restrict__ Kr, const bf16_t* __restrict__ Vs, bf16_t* Os, int q0, int Lp, char* lds, const int tid) {
;     ...
;     for (int j = 1; j + 1 < NT; j += 2) {
;         SBAR(); region_qk<true, true, 1>(pB0, pB1, K_lds + SHM_K, qr, qslot, kb, pA0, pA1, m_reg, alA, l_reg, pa, vb0, vl, vh, DMA_FN(j + 1, 0, j, 1));
;         if (j == 1) { asm volatile("" ::: "memory"); mask_48(pB0, pB1); }
;         region_pv<true, true>(o, vb0, pa, pB0, pB1, m_reg, alB, vl, vh); PIN2(pB0, pB1);
;         RESC(alB);
;         WAITV(0); LBAR();
;         SBAR(); region_qk<true, true, 1>(pA0, pA1, K_lds, qr, qslot, kb, pB0, pB1, m_reg, alB, l_reg, pa, vb0 + SHM_V, vl, vh, DMA_FN(j + 2, 1, j + 1, 0));
;         region_pv<true, true>(o, vb0 + SHM_V, pa, pA0, pA1, m_reg, alA, vl, vh); PIN2(pA0, pA1);
;         RESC(alA);
;         WAITV(0); LBAR();
;     }
.LBB0_632:
	s_add_u32 s42, s42, 0x80000
	s_waitcnt vmcnt(0)
	s_addc_u32 s43, s43, 0
	v_add_f32_e32 v80, v223, v225
	s_add_u32 s46, s46, 2
	v_fmac_f32_e32 v80, v219, v221
	v_add_f32_e32 v219, v92, v93
	s_addc_u32 s47, s47, 0
	v_fmac_f32_e32 v219, v80, v227
	s_cmp_ge_u32 s46, s71
	s_cbranch_scc1 .Lattn_exit_bar
	v_mov_b32_e32 v221, v131
	s_branch .Lattn_head_bar
